# c8_dispatch_shortcut_kprime_hoist
# speedup vs baseline: 1.0310x; 1.0097x over previous
.LBB0_1413:
	s_add_i32 s81, s31, 0
	s_add_i32 m0, s81, 0x4000
	v_lshl_add_u64 v[6:7], s[36:37], 0, v[36:37]
	s_add_i32 s22, s82, 0
	s_waitcnt vmcnt(0)
	s_waitcnt vmcnt(0) lgkmcnt(0)
	s_barrier
	global_load_lds_dwordx4 v[6:7], off
	v_lshl_add_u64 v[6:7], v[6:7], 0, s[14:15]
	s_add_i32 m0, s81, 0x6000
	s_add_i32 s22, s22, s27
	global_load_lds_dwordx4 v[6:7], off
	s_add_i32 m0, s22, 0x10200
	v_lshl_add_u64 v[0:1], v[0:1], 0, s[16:17]
	global_load_lds_dwordx4 v[0:1], off
	s_add_i32 s19, s19, s60
	v_or_b32_e32 v2, s19, v38
	v_cvt_f32_i32_e32 v161, v2
	v_lshrrev_b32_e32 v1, 3, v4
	v_bitop3_b32 v1, v1, v40, 1 bitop3:0x6c
	v_lshlrev_b32_e32 v1, 4, v1
	v_or_b32_e32 v2, 32, v38
	v_lshl_or_b32 v217, v38, 5, v1
	v_lshl_or_b32 v220, v2, 5, v1
	v_mul_f32_e64 v0, v210, -v161
	v_add_u32_e32 v41, 0, v220
	v_add_u32_e32 v50, 0, v217
	ds_read_b128 v[42:45], v41 offset:49152
	ds_read_b128 v[46:49], v50 offset:49152
	v_cvt_pk_bf16_f32 v0, v0, v3
	v_cvt_f32_ubyte0_e32 v218, v2
	v_lshlrev_b32_e32 v0, 16, v0
	v_fma_f32 v1, v210, -v161, -v0
	v_cvt_pk_bf16_f32 v2, v1, v3
	s_xor_b64 s[48:49], s[4:5], -1
	v_cmp_gt_u32_e64 s[4:5], 32, v39
	v_lshlrev_b32_e32 v2, 16, v2
	v_sub_f32_e32 v1, v1, v2
	v_cndmask_b32_e64 v164, 0, v207, s[4:5]
	v_cndmask_b32_e64 v163, 0, v208, s[4:5]
	v_cvt_f32_ubyte0_e32 v219, v38
	v_cvt_pk_bf16_f32 v248, v219, v219
	v_cvt_pk_bf16_f32 v252, v218, v218
	v_mov_b32_e32 v249, v163
	v_mov_b32_e32 v250, v164
	v_mov_b32_e32 v251, v3
	v_mov_b32_e32 v253, v163
	v_mov_b32_e32 v254, v164
	v_mov_b32_e32 v255, v3
	v_cndmask_b32_e64 v248, 0, v248, s[4:5]
	v_cndmask_b32_e64 v252, 0, v252, s[4:5]
	v_cvt_pk_bf16_f32 v0, v0, v2
	v_cvt_pk_bf16_f32 v1, v1, v3
	v_cvt_pk_bf16_f32 v4, v219, v219
	v_cvt_pk_bf16_f32 v5, v218, v218
	v_mov_b32_e32 v165, v3
	v_cndmask_b32_e64 v162, 0, v4, s[4:5]
	v_cndmask_b32_e64 v20, 0, v5, s[4:5]
	v_mov_b32_e32 v21, v163
	v_mov_b32_e32 v22, v164
	v_mov_b32_e32 v23, v3
	v_cndmask_b32_e64 v2, 0, v1, s[4:5]
	v_cndmask_b32_e64 v1, 0, v0, s[4:5]
	v_cndmask_b32_e64 v0, 0, v160, s[4:5]
	s_add_i32 s31, s19, 63
	s_cmpk_lt_u32 s31, 0x7f
	v_mfma_f32_32x32x16_bf16 v[4:19], v[162:165], v[0:3], 0
	s_cselect_b64 s[44:45], -1, 0
	s_cmpk_gt_i32 s19, 0xffc0
	s_mov_b64 s[52:53], -1
	v_mfma_f32_32x32x16_bf16 v[20:35], v[20:23], v[0:3], 0
	v_cndmask_b32_e64 v0, 0, 1, s[44:45]
	s_nop 0
	v_readfirstlane_b32 s31, v0
	s_cselect_b32 s31, s31, 2
	s_cmp_gt_i32 s31, 1
	s_waitcnt lgkmcnt(0)
	v_mfma_f32_32x32x16_bf16 v[4:19], v[46:49], v[156:159], v[4:19]
	v_mfma_f32_32x32x16_bf16 v[20:35], v[42:45], v[156:159], v[20:35]
	ds_read_b128 v[42:45], v41 offset:51264
	ds_read_b128 v[46:49], v50 offset:51264
	s_waitcnt lgkmcnt(0)
	v_mfma_f32_32x32x16_bf16 v[4:19], v[46:49], v[152:155], v[4:19]
	v_mfma_f32_32x32x16_bf16 v[20:35], v[42:45], v[152:155], v[20:35]
	ds_read_b128 v[42:45], v41 offset:53376
	ds_read_b128 v[46:49], v50 offset:53376
	s_waitcnt lgkmcnt(0)
	v_mfma_f32_32x32x16_bf16 v[4:19], v[46:49], v[148:151], v[4:19]
	v_mfma_f32_32x32x16_bf16 v[20:35], v[42:45], v[148:151], v[20:35]
	ds_read_b128 v[42:45], v41 offset:55488
	ds_read_b128 v[46:49], v50 offset:55488
	s_waitcnt lgkmcnt(0)
	v_mfma_f32_32x32x16_bf16 v[4:19], v[46:49], v[144:147], v[4:19]
	v_mfma_f32_32x32x16_bf16 v[20:35], v[42:45], v[144:147], v[20:35]
	s_cbranch_scc0 .LBB0_1415
	s_mov_b64 s[52:53], 0

.LBB0_1422:
	s_lshl_b32 s18, s44, 14
	s_add_i32 s52, s81, s18
	s_mov_b32 m0, s52
	v_lshl_add_u64 v[0:1], v[194:195], 0, s[14:15]
	global_load_lds_dwordx4 v[194:195], off
	s_add_i32 m0, s52, 0x2000
	s_mul_i32 s52, s54, 0x2100
	s_add_i32 s52, s22, s52
	global_load_lds_dwordx4 v[0:1], off
	s_add_i32 m0, s52, 0xc000
	s_add_i32 s52, s45, -1
	s_cmp_lt_u32 s52, s2
	s_cselect_b32 s55, s52, s3
	s_lshl_b32 s56, s55, 6
	v_mad_u64_u32 v[0:1], s[52:53], s56, v209, v[192:193]
	v_lshl_add_u64 v[0:1], v[0:1], 0, s[10:11]
	global_load_lds_dwordx4 v[0:1], off
	s_mul_i32 s52, s55, 0x60000
	s_mul_hi_u32 s53, s56, 0x1800
	s_mul_i32 s55, s69, 0x2100
	s_add_i32 s71, s55, 0
	s_sub_i32 s55, s65, 64
	v_cvt_f32_u32_e32 v0, s55
	v_add_u32_e32 v166, s71, v220
	v_add_u32_e32 v167, s71, v217
	ds_read_b128 v[4:7], v166 offset:49152
	ds_read_b128 v[8:11], v167 offset:49152
	v_sub_f32_e32 v196, v0, v161
	v_fma_f32 v0, v210, v196, -v221
	v_cvt_pk_bf16_f32 v1, v0, v3
	v_lshlrev_b32_e32 v1, 16, v1
	v_sub_f32_e32 v0, v0, v1
	v_cvt_pk_bf16_f32 v2, v0, v3
	v_lshlrev_b32_e32 v2, 16, v2
	v_sub_f32_e32 v0, v0, v2
	v_cvt_pk_bf16_f32 v1, v1, v2
	v_cvt_pk_bf16_f32 v0, v0, v3
	s_nop 0
	v_cndmask_b32_e64 v2, 0, v0, s[4:5]
	v_cndmask_b32_e64 v0, 0, v160, s[4:5]
	v_cndmask_b32_e64 v1, 0, v1, s[4:5]
	s_nop 1
	v_mfma_f32_32x32x16_bf16 v[128:143], v[248:251], v[0:3], 0
	v_mfma_f32_32x32x16_bf16 v[112:127], v[252:255], v[0:3], 0
	v_add_f32_e32 v1, 0, v96
	v_add_f32_e32 v1, v97, v1
	v_add_f32_e32 v1, v98, v1
	v_add_f32_e32 v1, v99, v1
	v_add_f32_e32 v1, v100, v1
	v_add_f32_e32 v1, v101, v1
	v_add_f32_e32 v1, v102, v1
	s_waitcnt lgkmcnt(0)
	v_mfma_f32_32x32x16_bf16 v[128:143], v[8:11], v[156:159], v[128:143]
	v_add_f32_e32 v1, v103, v1
	v_add_f32_e32 v1, v104, v1
	v_add_f32_e32 v1, v105, v1
	v_add_f32_e32 v1, v106, v1
	v_add_f32_e32 v1, v107, v1
	v_add_f32_e32 v1, v108, v1
	v_add_f32_e32 v1, v109, v1
	v_mfma_f32_32x32x16_bf16 v[112:127], v[4:7], v[156:159], v[112:127]
	ds_read_b128 v[4:7], v166 offset:51264
	ds_read_b128 v[8:11], v167 offset:51264
	v_add_f32_e32 v1, v110, v1
	v_add_f32_e32 v1, v111, v1
	v_add_f32_e32 v1, v80, v1
	v_add_f32_e32 v1, v81, v1
	v_add_f32_e32 v1, v82, v1
	v_add_f32_e32 v1, v83, v1
	s_waitcnt lgkmcnt(0)
	v_mfma_f32_32x32x16_bf16 v[128:143], v[8:11], v[152:155], v[128:143]
	v_add_f32_e32 v1, v84, v1
	v_add_f32_e32 v1, v85, v1
	v_add_f32_e32 v1, v86, v1
	v_add_f32_e32 v1, v87, v1
	v_add_f32_e32 v1, v88, v1
	v_add_f32_e32 v1, v89, v1
	v_add_f32_e32 v1, v90, v1
	v_mfma_f32_32x32x16_bf16 v[112:127], v[4:7], v[152:155], v[112:127]
	ds_read_b128 v[4:7], v166 offset:53376
	ds_read_b128 v[8:11], v167 offset:53376
	v_add_f32_e32 v1, v91, v1
	v_add_f32_e32 v1, v92, v1
	v_add_f32_e32 v1, v93, v1
	v_add_f32_e32 v1, v94, v1
	v_add_f32_e32 v223, v95, v1
	v_mov_b32_e32 v224, v223
	s_waitcnt lgkmcnt(0)
	v_mfma_f32_32x32x16_bf16 v[128:143], v[8:11], v[148:151], v[128:143]
	v_permlane32_swap_b32_e32 v223, v224
	v_mfma_f32_32x32x16_bf16 v[112:127], v[4:7], v[148:151], v[112:127]
	ds_read_b128 v[4:7], v166 offset:55488
	ds_read_b128 v[8:11], v167 offset:55488
	v_cvt_pk_bf16_f32 v166, v96, v97
	v_cvt_pk_bf16_f32 v167, v98, v99
	v_cvt_pk_bf16_f32 v168, v100, v101
	v_cvt_pk_bf16_f32 v169, v102, v103
	v_cvt_pk_bf16_f32 v12, v104, v105
	v_cvt_pk_bf16_f32 v13, v106, v107
	s_waitcnt lgkmcnt(0)
	v_mfma_f32_32x32x16_bf16 v[128:143], v[8:11], v[144:147], v[128:143]
	v_cvt_pk_bf16_f32 v14, v108, v109
	v_cvt_pk_bf16_f32 v15, v110, v111
	v_cvt_pk_bf16_f32 v8, v80, v81
	v_cvt_pk_bf16_f32 v9, v82, v83
	v_cvt_pk_bf16_f32 v10, v84, v85
	v_cvt_pk_bf16_f32 v11, v86, v87
	v_mfma_f32_32x32x16_bf16 v[112:127], v[4:7], v[144:147], v[112:127]
	v_cvt_pk_bf16_f32 v4, v88, v89
	v_cvt_pk_bf16_f32 v5, v90, v91
	v_cvt_pk_bf16_f32 v6, v92, v93
	v_cvt_pk_bf16_f32 v7, v94, v95
	v_lshl_add_u32 v1, s54, 14, v215
	ds_read_b64_tr_b16 v[182:183], v1 offset:0
	ds_read_b64_tr_b16 v[184:185], v1 offset:0x800
	ds_read_b64_tr_b16 v[178:179], v1 offset:0x1000
	ds_read_b64_tr_b16 v[180:181], v1 offset:0x1800
	s_add_i32 s70, s45, -3
	s_add_i32 s54, s19, s45
	ds_read_b64_tr_b16 v[174:175], v1 offset:0x2000
	s_cmp_eq_u32 s54, 3
	ds_read_b64_tr_b16 v[176:177], v1 offset:0x2800
	s_cselect_b64 s[54:55], -1, 0
	ds_read_b64_tr_b16 v[170:171], v1 offset:0x3000
	v_cndmask_b32_e64 v2, 0, 1, s[54:55]
	ds_read_b64_tr_b16 v[172:173], v1 offset:0x3800
	s_cmp_lt_i32 s70, s31
	s_cbranch_scc1 .Lf_odd
	s_cmp_le_i32 s70, s31
	v_readfirstlane_b32 s54, v2
	s_cselect_b32 s66, s54, 2
	s_cmp_gt_i32 s66, 1
	s_cbranch_scc0 .LBB0_1425
	s_mov_b64 s[54:55], -1
	v_mov_b32_e32 v197, 0xf149f2ca
	s_cbranch_execz .LBB0_1426
	v_mov_b32_e32 v142, 0xf149f2ca
	v_mov_b32_e32 v141, 0xf149f2ca
	v_mov_b32_e32 v140, 0xf149f2ca
	v_mov_b32_e32 v139, 0xf149f2ca
	v_mov_b32_e32 v138, 0xf149f2ca
	v_mov_b32_e32 v137, 0xf149f2ca
	v_mov_b32_e32 v136, 0xf149f2ca
	v_mov_b32_e32 v135, 0xf149f2ca
	v_mov_b32_e32 v134, 0xf149f2ca
	v_mov_b32_e32 v133, 0xf149f2ca
	v_mov_b32_e32 v132, 0xf149f2ca
	v_mov_b32_e32 v131, 0xf149f2ca
	v_mov_b32_e32 v130, 0xf149f2ca
	v_mov_b32_e32 v129, 0xf149f2ca
	v_mov_b32_e32 v128, 0xf149f2ca
	v_mov_b32_e32 v127, 0xf149f2ca
	v_mov_b32_e32 v126, 0xf149f2ca
	v_mov_b32_e32 v125, 0xf149f2ca
	v_mov_b32_e32 v124, 0xf149f2ca
	v_mov_b32_e32 v123, 0xf149f2ca
	v_mov_b32_e32 v122, 0xf149f2ca
	v_mov_b32_e32 v121, 0xf149f2ca
	v_mov_b32_e32 v120, 0xf149f2ca
	v_mov_b32_e32 v119, 0xf149f2ca
	v_mov_b32_e32 v118, 0xf149f2ca
	v_mov_b32_e32 v117, 0xf149f2ca
	v_mov_b32_e32 v116, 0xf149f2ca
	v_mov_b32_e32 v115, 0xf149f2ca
	v_mov_b32_e32 v114, 0xf149f2ca
	v_mov_b32_e32 v113, 0xf149f2ca
	v_mov_b32_e32 v112, 0xf149f2ca
	s_and_b64 vcc, exec, s[54:55]
	s_cbranch_vccnz .LBB0_1429
	s_branch .LBB0_1430

.LBB0_1437:
	s_waitcnt vmcnt(0)
	s_add_i32 s54, s44, 1
	s_cmp_lg_u32 s44, 2
	s_cselect_b32 s67, s54, 0
	s_waitcnt vmcnt(0)
	s_barrier
	s_lshl_b32 s66, s67, 14
	s_add_i32 s54, s81, s66
	v_lshl_add_u64 v[4:5], v[190:191], 0, s[52:53]
	s_mov_b32 m0, s54
	s_add_i32 s52, s71, s82
	global_load_lds_dwordx4 v[4:5], off
	v_lshl_add_u64 v[4:5], v[4:5], 0, s[14:15]
	s_add_i32 m0, s54, 0x2000
	s_add_i32 s52, s52, s27
	global_load_lds_dwordx4 v[4:5], off
	s_add_i32 m0, s52, 0xc000
	s_cmp_ge_u32 s45, s2
	s_cselect_b64 s[52:53], -1, 0
	s_cmp_lt_u32 s45, s2
	s_cselect_b32 s54, s45, s3
	s_lshl_b32 s54, s54, 6
	v_mad_u64_u32 v[4:5], s[54:55], s54, v209, v[192:193]
	v_lshl_add_u64 v[4:5], v[4:5], 0, s[10:11]
	global_load_lds_dwordx4 v[4:5], off
	v_cvt_f32_u32_e32 v1, s65
	s_mul_i32 s54, s44, 0x2100
	s_add_i32 s54, s54, 0
	v_add_u32_e32 v166, s54, v220
	v_sub_f32_e32 v196, v1, v161
	v_add_u32_e32 v167, s54, v217
	v_fma_f32 v1, v210, v196, -v221
	ds_read_b128 v[4:7], v166 offset:49152
	ds_read_b128 v[8:11], v167 offset:49152
	v_cvt_pk_bf16_f32 v2, v1, v3
	v_lshlrev_b32_e32 v2, 16, v2
	v_sub_f32_e32 v1, v1, v2
	v_cvt_pk_bf16_f32 v12, v1, v3
	v_lshlrev_b32_e32 v12, 16, v12
	v_sub_f32_e32 v1, v1, v12
	v_cvt_pk_bf16_f32 v12, v2, v12
	v_cvt_pk_bf16_f32 v1, v1, v3
	s_nop 0
	v_cndmask_b32_e64 v2, 0, v1, s[4:5]
	v_cndmask_b32_e64 v1, 0, v12, s[4:5]
	s_nop 1
	v_mfma_f32_32x32x16_bf16 v[128:143], v[248:251], v[0:3], 0
	s_nop 0
	v_mfma_f32_32x32x16_bf16 v[112:127], v[252:255], v[0:3], 0
	v_add_f32_e32 v1, 0, v96
	v_add_f32_e32 v1, v97, v1
	v_add_f32_e32 v1, v98, v1
	v_add_f32_e32 v1, v99, v1
	v_add_f32_e32 v1, v100, v1
	v_add_f32_e32 v1, v101, v1
	v_add_f32_e32 v1, v102, v1
	s_waitcnt lgkmcnt(0)
	v_mfma_f32_32x32x16_bf16 v[128:143], v[8:11], v[156:159], v[128:143]
	v_add_f32_e32 v1, v103, v1
	v_add_f32_e32 v1, v104, v1
	v_add_f32_e32 v1, v105, v1
	v_add_f32_e32 v1, v106, v1
	v_add_f32_e32 v1, v107, v1
	v_add_f32_e32 v1, v108, v1
	v_add_f32_e32 v1, v109, v1
	v_mfma_f32_32x32x16_bf16 v[112:127], v[4:7], v[156:159], v[112:127]
	ds_read_b128 v[4:7], v166 offset:51264
	ds_read_b128 v[8:11], v167 offset:51264
	v_add_f32_e32 v1, v110, v1
	v_add_f32_e32 v1, v111, v1
	v_add_f32_e32 v1, v80, v1
	v_add_f32_e32 v1, v81, v1
	v_add_f32_e32 v1, v82, v1
	v_add_f32_e32 v1, v83, v1
	s_waitcnt lgkmcnt(0)
	v_mfma_f32_32x32x16_bf16 v[128:143], v[8:11], v[152:155], v[128:143]
	v_add_f32_e32 v1, v84, v1
	v_add_f32_e32 v1, v85, v1
	v_add_f32_e32 v1, v86, v1
	v_add_f32_e32 v1, v87, v1
	v_add_f32_e32 v1, v88, v1
	v_add_f32_e32 v1, v89, v1
	v_add_f32_e32 v1, v90, v1
	v_mfma_f32_32x32x16_bf16 v[112:127], v[4:7], v[152:155], v[112:127]
	ds_read_b128 v[4:7], v166 offset:53376
	ds_read_b128 v[8:11], v167 offset:53376
	v_add_f32_e32 v1, v91, v1
	v_add_f32_e32 v1, v92, v1
	v_add_f32_e32 v1, v93, v1
	v_add_f32_e32 v1, v94, v1
	v_add_f32_e32 v1, v95, v1
	v_mov_b32_e32 v2, v1
	s_waitcnt lgkmcnt(0)
	v_mfma_f32_32x32x16_bf16 v[128:143], v[8:11], v[148:151], v[128:143]
	v_permlane32_swap_b32_e32 v1, v2
	v_mfma_f32_32x32x16_bf16 v[112:127], v[4:7], v[148:151], v[112:127]
	ds_read_b128 v[4:7], v166 offset:55488
	ds_read_b128 v[8:11], v167 offset:55488
	v_cvt_pk_bf16_f32 v166, v96, v97
	v_cvt_pk_bf16_f32 v167, v98, v99
	v_cvt_pk_bf16_f32 v168, v100, v101
	v_cvt_pk_bf16_f32 v169, v102, v103
	v_cvt_pk_bf16_f32 v12, v104, v105
	v_cvt_pk_bf16_f32 v13, v106, v107
	s_waitcnt lgkmcnt(0)
	v_mfma_f32_32x32x16_bf16 v[128:143], v[8:11], v[144:147], v[128:143]
	v_cvt_pk_bf16_f32 v14, v108, v109
	v_cvt_pk_bf16_f32 v15, v110, v111
	v_cvt_pk_bf16_f32 v8, v80, v81
	v_cvt_pk_bf16_f32 v9, v82, v83
	v_cvt_pk_bf16_f32 v10, v84, v85
	v_cvt_pk_bf16_f32 v11, v86, v87
	v_mfma_f32_32x32x16_bf16 v[112:127], v[4:7], v[144:147], v[112:127]
	v_cvt_pk_bf16_f32 v4, v88, v89
	v_cvt_pk_bf16_f32 v5, v90, v91
	v_cvt_pk_bf16_f32 v6, v92, v93
	v_cvt_pk_bf16_f32 v7, v94, v95
	v_lshl_add_u32 v162, s69, 14, v215
	ds_read_b64_tr_b16 v[182:183], v162 offset:0
	ds_read_b64_tr_b16 v[184:185], v162 offset:0x800
	ds_read_b64_tr_b16 v[178:179], v162 offset:0x1000
	ds_read_b64_tr_b16 v[180:181], v162 offset:0x1800
	s_add_i32 s54, s64, s45
	ds_read_b64_tr_b16 v[174:175], v162 offset:0x2000
	s_cmp_eq_u32 s54, 4
	ds_read_b64_tr_b16 v[176:177], v162 offset:0x2800
	s_cselect_b64 s[54:55], -1, 0
	ds_read_b64_tr_b16 v[170:171], v162 offset:0x3000
	v_cndmask_b32_e64 v80, 0, 1, s[54:55]
	ds_read_b64_tr_b16 v[172:173], v162 offset:0x3800
	s_add_i32 s98, s70, 2
	s_cmp_le_i32 s98, s31
	s_cbranch_scc1 .Lf_even
	s_cmp_lt_i32 s70, s31
	v_readfirstlane_b32 s54, v80
	s_cselect_b32 s69, s54, 2
	s_cmp_gt_i32 s69, 1
	s_cbranch_scc0 .LBB0_1440
	s_mov_b64 s[54:55], -1
	v_mov_b32_e32 v197, 0xf149f2ca
	s_cbranch_execz .LBB0_1441
	v_mov_b32_e32 v142, 0xf149f2ca
	v_mov_b32_e32 v141, 0xf149f2ca
	v_mov_b32_e32 v140, 0xf149f2ca
	v_mov_b32_e32 v139, 0xf149f2ca
	v_mov_b32_e32 v138, 0xf149f2ca
	v_mov_b32_e32 v137, 0xf149f2ca
	v_mov_b32_e32 v136, 0xf149f2ca
	v_mov_b32_e32 v135, 0xf149f2ca
	v_mov_b32_e32 v134, 0xf149f2ca
	v_mov_b32_e32 v133, 0xf149f2ca
	v_mov_b32_e32 v132, 0xf149f2ca
	v_mov_b32_e32 v131, 0xf149f2ca
	v_mov_b32_e32 v130, 0xf149f2ca
	v_mov_b32_e32 v129, 0xf149f2ca
	v_mov_b32_e32 v128, 0xf149f2ca
	v_mov_b32_e32 v127, 0xf149f2ca
	v_mov_b32_e32 v126, 0xf149f2ca
	v_mov_b32_e32 v125, 0xf149f2ca
	v_mov_b32_e32 v124, 0xf149f2ca
	v_mov_b32_e32 v123, 0xf149f2ca
	v_mov_b32_e32 v122, 0xf149f2ca
	v_mov_b32_e32 v121, 0xf149f2ca
	v_mov_b32_e32 v120, 0xf149f2ca
	v_mov_b32_e32 v119, 0xf149f2ca
	v_mov_b32_e32 v118, 0xf149f2ca
	v_mov_b32_e32 v117, 0xf149f2ca
	v_mov_b32_e32 v116, 0xf149f2ca
	v_mov_b32_e32 v115, 0xf149f2ca
	v_mov_b32_e32 v114, 0xf149f2ca
	v_mov_b32_e32 v113, 0xf149f2ca
	v_mov_b32_e32 v112, 0xf149f2ca
	s_and_b64 vcc, exec, s[54:55]
	s_cbranch_vccnz .LBB0_1444
	s_branch .LBB0_1445

	.amdhsa_kernel _Z8mega_fwd4Args
		.amdhsa_group_segment_fixed_size 0
		.amdhsa_private_segment_fixed_size 0
		.amdhsa_kernarg_size 440
		.amdhsa_user_sgpr_count 2
		.amdhsa_user_sgpr_dispatch_ptr 0
		.amdhsa_user_sgpr_queue_ptr 0
		.amdhsa_user_sgpr_kernarg_segment_ptr 1
		.amdhsa_user_sgpr_dispatch_id 0
		.amdhsa_user_sgpr_kernarg_preload_length 0
		.amdhsa_user_sgpr_kernarg_preload_offset 0
		.amdhsa_user_sgpr_private_segment_size 0
		.amdhsa_uses_dynamic_stack 0
		.amdhsa_enable_private_segment 0
		.amdhsa_system_sgpr_workgroup_id_x 1
		.amdhsa_system_sgpr_workgroup_id_y 0
		.amdhsa_system_sgpr_workgroup_id_z 0
		.amdhsa_system_sgpr_workgroup_info 0
		.amdhsa_system_vgpr_workitem_id 2
		.amdhsa_next_free_vgpr 256
		.amdhsa_next_free_sgpr 102
		.amdhsa_accum_offset 256
		.amdhsa_reserve_vcc 1
		.amdhsa_float_round_mode_32 0
		.amdhsa_float_round_mode_16_64 0
		.amdhsa_float_denorm_mode_32 3
		.amdhsa_float_denorm_mode_16_64 3
		.amdhsa_dx10_clamp 1
		.amdhsa_ieee_mode 1
		.amdhsa_fp16_overflow 0
		.amdhsa_tg_split 0
		.amdhsa_exception_fp_ieee_invalid_op 0
		.amdhsa_exception_fp_denorm_src 0
		.amdhsa_exception_fp_ieee_div_zero 0
		.amdhsa_exception_fp_ieee_overflow 0
		.amdhsa_exception_fp_ieee_underflow 0
		.amdhsa_exception_fp_ieee_inexact 0
		.amdhsa_exception_int_div_zero 0
	.end_amdhsa_kernel

amdhsa.kernels:
  - .agpr_count:     0
    .args:
      - .offset:         0
        .size:           184
        .value_kind:     by_value
      - .offset:         184
        .size:           4
        .value_kind:     hidden_block_count_x
      - .offset:         188
        .size:           4
        .value_kind:     hidden_block_count_y
      - .offset:         192
        .size:           4
        .value_kind:     hidden_block_count_z
      - .offset:         196
        .size:           2
        .value_kind:     hidden_group_size_x
      - .offset:         198
        .size:           2
        .value_kind:     hidden_group_size_y
      - .offset:         200
        .size:           2
        .value_kind:     hidden_group_size_z
      - .offset:         202
        .size:           2
        .value_kind:     hidden_remainder_x
      - .offset:         204
        .size:           2
        .value_kind:     hidden_remainder_y
      - .offset:         206
        .size:           2
        .value_kind:     hidden_remainder_z
      - .offset:         224
        .size:           8
        .value_kind:     hidden_global_offset_x
      - .offset:         232
        .size:           8
        .value_kind:     hidden_global_offset_y
      - .offset:         240
        .size:           8
        .value_kind:     hidden_global_offset_z
      - .offset:         248
        .size:           2
        .value_kind:     hidden_grid_dims
      - .offset:         272
        .size:           8
        .value_kind:     hidden_multigrid_sync_arg
      - .offset:         304
        .size:           4
        .value_kind:     hidden_dynamic_lds_size
    .group_segment_fixed_size: 0
    .kernarg_segment_align: 8
    .kernarg_segment_size: 440
    .language:       OpenCL C
    .language_version:
      - 2
      - 0
    .max_flat_workgroup_size: 512
    .name:           _Z8mega_fwd4Args
    .private_segment_fixed_size: 0
    .sgpr_count:     108
    .sgpr_spill_count: 37
    .symbol:         _Z8mega_fwd4Args.kd
    .uniform_work_group_size: 1
    .uses_dynamic_stack: false
    .vgpr_count:     256
    .vgpr_spill_count: 0
    .wavefront_size: 64
